# deferred x conversion: streaming (nt) stores for the converted rows so they do not sit dirty in L2 until the barrier flush
# speedup vs baseline: 1.0025x; 1.0024x over previous
; __device__ __forceinline__ unsigned cvt_pk_bf16(float lo, float hi) { unsigned r; asm volatile("v_cvt_pk_bf16_f32 %0, %1, %2" : "=v"(r) : "v"(lo), "v"(hi)); return r; }
; #define GAS __attribute__((address_space(1)))
; __device__ __forceinline__ void phase_prep(const Params& P, unsigned char* smem) {
;     ...
;     for (int rid = gw; rid < NSEG * RSB; rid += NGW) {
;         const int s = rid / RSB, lr = rid % RSB; const float* src = nullptr;
;         if (lr < RS) src = P.x + ((size_t)(lr / TSEG) * SEQ + (size_t)s * TSEG + (lr % TSEG)) * DM;
;         else if (s == 0) { if (lr >= RS + 48 && lr < RS + 64) src = P.meta + (size_t)(lr - RS - 48) * DM; }
;         else continue;
;         GAS v2u* o8 = (GAS v2u*)(xb + (size_t)rid * DM) + lane; float ss = 0.f;
;         if (src) { const f32x4* xr = (const f32x4*)src + lane;
; #pragma unroll
;             for (int j = 0; j < 8; ++j) { const f32x4 v = __builtin_nontemporal_load((const GAS f32x4*)xr + 64 * j); ss += (v[0] * v[0] + v[1] * v[1]) + (v[2] * v[2] + v[3] * v[3]); v2u o; o.x = cvt_pk_bf16(v[0], v[1]); o.y = cvt_pk_bf16(v[2], v[3]); o8[64 * j] = o; } }
;         else {
; #pragma unroll
;             for (int j = 0; j < 8; ++j) { v2u o; o.x = 0u; o.y = 0u; o8[64 * j] = o; } }
;         ss = wave_sum(ss);
;         if (lane == 0) rstd1[rid] = rsqrtf(ss * (1.f / DM) + EPS);
.Lxc_loop:
	s_add_i32 s54, s9, s14
	s_cmp_lt_u32 s54, 0x2000
	s_cbranch_scc0 .Lxc_lastA
	s_lshr_b32 s20, s54, 12
	s_and_b32 s22, s54, 0xfff
	s_lshl_b32 s20, s20, 14
	s_add_i32 s20, s20, s22
	s_add_i32 s20, s20, s15
	s_lshl_b32 s20, s20, 13
	s_add_u32 s40, s16, s20
	s_addc_u32 s41, s17, 0
	global_load_dwordx4 v[72:75], v28, s[40:41] nt
	global_load_dwordx4 v[76:79], v28, s[40:41] offset:1024 nt
	global_load_dwordx4 v[80:83], v28, s[40:41] offset:2048 nt
	global_load_dwordx4 v[84:87], v28, s[40:41] offset:3072 nt
	global_load_dwordx4 v[88:91], v29, s[40:41] nt
	global_load_dwordx4 v[92:95], v29, s[40:41] offset:1024 nt
	global_load_dwordx4 v[96:99], v29, s[40:41] offset:2048 nt
	global_load_dwordx4 v[100:103], v29, s[40:41] offset:3072 nt
	s_waitcnt vmcnt(8)
	s_add_i32 s22, s9, s23
	s_lshl_b32 s24, s22, 12
	s_add_u32 s42, s48, s24
	s_addc_u32 s43, s49, 0
	s_lshl_b32 s24, s22, 2
	s_add_u32 s50, s52, s24
	s_addc_u32 s51, s53, 0
	v_pk_mul_f32 v[24:25], v[40:41], v[40:41]
	v_cvt_pk_bf16_f32 v8, v40, v41
	v_pk_fma_f32 v[24:25], v[42:43], v[42:43], v[24:25]
	v_cvt_pk_bf16_f32 v9, v42, v43
	global_store_dwordx2 v30, v[8:9], s[42:43] nt
	v_pk_fma_f32 v[24:25], v[44:45], v[44:45], v[24:25]
	v_cvt_pk_bf16_f32 v10, v44, v45
	v_pk_fma_f32 v[24:25], v[46:47], v[46:47], v[24:25]
	v_cvt_pk_bf16_f32 v11, v46, v47
	global_store_dwordx2 v30, v[10:11], s[42:43] offset:512 nt
	v_pk_fma_f32 v[24:25], v[48:49], v[48:49], v[24:25]
	v_cvt_pk_bf16_f32 v12, v48, v49
	v_pk_fma_f32 v[24:25], v[50:51], v[50:51], v[24:25]
	v_cvt_pk_bf16_f32 v13, v50, v51
	global_store_dwordx2 v30, v[12:13], s[42:43] offset:1024 nt
	v_pk_fma_f32 v[24:25], v[52:53], v[52:53], v[24:25]
	v_cvt_pk_bf16_f32 v14, v52, v53
	v_pk_fma_f32 v[24:25], v[54:55], v[54:55], v[24:25]
	v_cvt_pk_bf16_f32 v15, v54, v55
	global_store_dwordx2 v30, v[14:15], s[42:43] offset:1536 nt
	v_pk_fma_f32 v[24:25], v[56:57], v[56:57], v[24:25]
	v_cvt_pk_bf16_f32 v16, v56, v57
	v_pk_fma_f32 v[24:25], v[58:59], v[58:59], v[24:25]
	v_cvt_pk_bf16_f32 v17, v58, v59
	global_store_dwordx2 v30, v[16:17], s[42:43] offset:2048 nt
	v_pk_fma_f32 v[24:25], v[60:61], v[60:61], v[24:25]
	v_cvt_pk_bf16_f32 v18, v60, v61
	v_pk_fma_f32 v[24:25], v[62:63], v[62:63], v[24:25]
	v_cvt_pk_bf16_f32 v19, v62, v63
	global_store_dwordx2 v30, v[18:19], s[42:43] offset:2560 nt
	v_pk_fma_f32 v[24:25], v[64:65], v[64:65], v[24:25]
	v_cvt_pk_bf16_f32 v20, v64, v65
	v_pk_fma_f32 v[24:25], v[66:67], v[66:67], v[24:25]
	v_cvt_pk_bf16_f32 v21, v66, v67
	global_store_dwordx2 v30, v[20:21], s[42:43] offset:3072 nt
	v_pk_fma_f32 v[24:25], v[68:69], v[68:69], v[24:25]
	v_cvt_pk_bf16_f32 v22, v68, v69
	v_pk_fma_f32 v[24:25], v[70:71], v[70:71], v[24:25]
	v_cvt_pk_bf16_f32 v23, v70, v71
	global_store_dwordx2 v30, v[22:23], s[42:43] offset:3584 nt
	v_add_f32_e32 v26, v24, v25
	s_nop 1
	v_add_f32_dpp v26, v26, v26 quad_perm:[1,0,3,2] row_mask:0xf bank_mask:0xf
	s_nop 1
	v_add_f32_dpp v26, v26, v26 quad_perm:[2,3,0,1] row_mask:0xf bank_mask:0xf
	s_nop 1
	v_add_f32_dpp v26, v26, v26 row_half_mirror row_mask:0xf bank_mask:0xf
	s_nop 1
	v_add_f32_dpp v26, v26, v26 row_mirror row_mask:0xf bank_mask:0xf
	s_nop 1
	v_add_f32_dpp v26, v26, v26 row_bcast:15 row_mask:0xa bank_mask:0xf
	s_nop 1
	v_add_f32_dpp v26, v26, v26 row_bcast:31 row_mask:0xc bank_mask:0xf
	s_nop 1
	v_readlane_b32 s24, v26, 63
	s_nop 3
	v_fma_f32 v26, s24, v32, v33
	v_rsq_f32_e32 v26, v26
	s_mov_b64 exec, 1
	s_nop 1
	global_store_dword v31, v26, s[50:51]
	s_mov_b64 exec, -1
	s_mov_b32 s9, s54
	s_add_i32 s54, s9, s14
	s_cmp_lt_u32 s54, 0x2000
	s_cbranch_scc0 .Lxc_lastB
	s_lshr_b32 s20, s54, 12
	s_and_b32 s22, s54, 0xfff
	s_lshl_b32 s20, s20, 14
	s_add_i32 s20, s20, s22
	s_add_i32 s20, s20, s15
	s_lshl_b32 s20, s20, 13
	s_add_u32 s40, s16, s20
	s_addc_u32 s41, s17, 0
	global_load_dwordx4 v[40:43], v28, s[40:41] nt
	global_load_dwordx4 v[44:47], v28, s[40:41] offset:1024 nt
	global_load_dwordx4 v[48:51], v28, s[40:41] offset:2048 nt
	global_load_dwordx4 v[52:55], v28, s[40:41] offset:3072 nt
	global_load_dwordx4 v[56:59], v29, s[40:41] nt
	global_load_dwordx4 v[60:63], v29, s[40:41] offset:1024 nt
	global_load_dwordx4 v[64:67], v29, s[40:41] offset:2048 nt
	global_load_dwordx4 v[68:71], v29, s[40:41] offset:3072 nt
	s_waitcnt vmcnt(8)
	s_add_i32 s22, s9, s23
	s_lshl_b32 s24, s22, 12
	s_add_u32 s42, s48, s24
	s_addc_u32 s43, s49, 0
	s_lshl_b32 s24, s22, 2
	s_add_u32 s50, s52, s24
	s_addc_u32 s51, s53, 0
	v_pk_mul_f32 v[24:25], v[72:73], v[72:73]
	v_cvt_pk_bf16_f32 v8, v72, v73
	v_pk_fma_f32 v[24:25], v[74:75], v[74:75], v[24:25]
	v_cvt_pk_bf16_f32 v9, v74, v75
	global_store_dwordx2 v30, v[8:9], s[42:43] nt
	v_pk_fma_f32 v[24:25], v[76:77], v[76:77], v[24:25]
	v_cvt_pk_bf16_f32 v10, v76, v77
	v_pk_fma_f32 v[24:25], v[78:79], v[78:79], v[24:25]
	v_cvt_pk_bf16_f32 v11, v78, v79
	global_store_dwordx2 v30, v[10:11], s[42:43] offset:512 nt
	v_pk_fma_f32 v[24:25], v[80:81], v[80:81], v[24:25]
	v_cvt_pk_bf16_f32 v12, v80, v81
	v_pk_fma_f32 v[24:25], v[82:83], v[82:83], v[24:25]
	v_cvt_pk_bf16_f32 v13, v82, v83
	global_store_dwordx2 v30, v[12:13], s[42:43] offset:1024 nt
	v_pk_fma_f32 v[24:25], v[84:85], v[84:85], v[24:25]
	v_cvt_pk_bf16_f32 v14, v84, v85
	v_pk_fma_f32 v[24:25], v[86:87], v[86:87], v[24:25]
	v_cvt_pk_bf16_f32 v15, v86, v87
	global_store_dwordx2 v30, v[14:15], s[42:43] offset:1536 nt
	v_pk_fma_f32 v[24:25], v[88:89], v[88:89], v[24:25]
	v_cvt_pk_bf16_f32 v16, v88, v89
	v_pk_fma_f32 v[24:25], v[90:91], v[90:91], v[24:25]
	v_cvt_pk_bf16_f32 v17, v90, v91
	global_store_dwordx2 v30, v[16:17], s[42:43] offset:2048 nt
	v_pk_fma_f32 v[24:25], v[92:93], v[92:93], v[24:25]
	v_cvt_pk_bf16_f32 v18, v92, v93
	v_pk_fma_f32 v[24:25], v[94:95], v[94:95], v[24:25]
	v_cvt_pk_bf16_f32 v19, v94, v95
	global_store_dwordx2 v30, v[18:19], s[42:43] offset:2560 nt
	v_pk_fma_f32 v[24:25], v[96:97], v[96:97], v[24:25]
	v_cvt_pk_bf16_f32 v20, v96, v97
	v_pk_fma_f32 v[24:25], v[98:99], v[98:99], v[24:25]
	v_cvt_pk_bf16_f32 v21, v98, v99
	global_store_dwordx2 v30, v[20:21], s[42:43] offset:3072 nt
	v_pk_fma_f32 v[24:25], v[100:101], v[100:101], v[24:25]
	v_cvt_pk_bf16_f32 v22, v100, v101
	v_pk_fma_f32 v[24:25], v[102:103], v[102:103], v[24:25]
	v_cvt_pk_bf16_f32 v23, v102, v103
	global_store_dwordx2 v30, v[22:23], s[42:43] offset:3584 nt
	v_add_f32_e32 v26, v24, v25
	s_nop 1
	v_add_f32_dpp v26, v26, v26 quad_perm:[1,0,3,2] row_mask:0xf bank_mask:0xf
	s_nop 1
	v_add_f32_dpp v26, v26, v26 quad_perm:[2,3,0,1] row_mask:0xf bank_mask:0xf
	s_nop 1
	v_add_f32_dpp v26, v26, v26 row_half_mirror row_mask:0xf bank_mask:0xf
	s_nop 1
	v_add_f32_dpp v26, v26, v26 row_mirror row_mask:0xf bank_mask:0xf
	s_nop 1
	v_add_f32_dpp v26, v26, v26 row_bcast:15 row_mask:0xa bank_mask:0xf
	s_nop 1
	v_add_f32_dpp v26, v26, v26 row_bcast:31 row_mask:0xc bank_mask:0xf
	s_nop 1
	v_readlane_b32 s24, v26, 63
	s_nop 3
	v_fma_f32 v26, s24, v32, v33
	v_rsq_f32_e32 v26, v26
	s_mov_b64 exec, 1
	s_nop 1
	global_store_dword v31, v26, s[50:51]
	s_mov_b64 exec, -1
	s_mov_b32 s9, s54
	s_branch .Lxc_loop
; __device__ __forceinline__ unsigned cvt_pk_bf16(float lo, float hi) { unsigned r; asm volatile("v_cvt_pk_bf16_f32 %0, %1, %2" : "=v"(r) : "v"(lo), "v"(hi)); return r; }
; #define GAS __attribute__((address_space(1)))
; __device__ __forceinline__ void phase_prep(const Params& P, unsigned char* smem) {
;     ...
;         GAS v2u* o8 = (GAS v2u*)(xb + (size_t)rid * DM) + lane; float ss = 0.f;
;         if (src) { const f32x4* xr = (const f32x4*)src + lane;
; #pragma unroll
;             for (int j = 0; j < 8; ++j) { const f32x4 v = __builtin_nontemporal_load((const GAS f32x4*)xr + 64 * j); ss += (v[0] * v[0] + v[1] * v[1]) + (v[2] * v[2] + v[3] * v[3]); v2u o; o.x = cvt_pk_bf16(v[0], v[1]); o.y = cvt_pk_bf16(v[2], v[3]); o8[64 * j] = o; } }
;         else {
; #pragma unroll
;             for (int j = 0; j < 8; ++j) { v2u o; o.x = 0u; o.y = 0u; o8[64 * j] = o; } }
;         ss = wave_sum(ss);
;         if (lane == 0) rstd1[rid] = rsqrtf(ss * (1.f / DM) + EPS);
.Lxc_lastA:
	s_waitcnt vmcnt(0)
	s_add_i32 s22, s9, s23
	s_lshl_b32 s24, s22, 12
	s_add_u32 s42, s48, s24
	s_addc_u32 s43, s49, 0
	s_lshl_b32 s24, s22, 2
	s_add_u32 s50, s52, s24
	s_addc_u32 s51, s53, 0
	v_pk_mul_f32 v[24:25], v[40:41], v[40:41]
	v_cvt_pk_bf16_f32 v8, v40, v41
	v_pk_fma_f32 v[24:25], v[42:43], v[42:43], v[24:25]
	v_cvt_pk_bf16_f32 v9, v42, v43
	global_store_dwordx2 v30, v[8:9], s[42:43] nt
	v_pk_fma_f32 v[24:25], v[44:45], v[44:45], v[24:25]
	v_cvt_pk_bf16_f32 v10, v44, v45
	v_pk_fma_f32 v[24:25], v[46:47], v[46:47], v[24:25]
	v_cvt_pk_bf16_f32 v11, v46, v47
	global_store_dwordx2 v30, v[10:11], s[42:43] offset:512 nt
	v_pk_fma_f32 v[24:25], v[48:49], v[48:49], v[24:25]
	v_cvt_pk_bf16_f32 v12, v48, v49
	v_pk_fma_f32 v[24:25], v[50:51], v[50:51], v[24:25]
	v_cvt_pk_bf16_f32 v13, v50, v51
	global_store_dwordx2 v30, v[12:13], s[42:43] offset:1024 nt
	v_pk_fma_f32 v[24:25], v[52:53], v[52:53], v[24:25]
	v_cvt_pk_bf16_f32 v14, v52, v53
	v_pk_fma_f32 v[24:25], v[54:55], v[54:55], v[24:25]
	v_cvt_pk_bf16_f32 v15, v54, v55
	global_store_dwordx2 v30, v[14:15], s[42:43] offset:1536 nt
	v_pk_fma_f32 v[24:25], v[56:57], v[56:57], v[24:25]
	v_cvt_pk_bf16_f32 v16, v56, v57
	v_pk_fma_f32 v[24:25], v[58:59], v[58:59], v[24:25]
	v_cvt_pk_bf16_f32 v17, v58, v59
	global_store_dwordx2 v30, v[16:17], s[42:43] offset:2048 nt
	v_pk_fma_f32 v[24:25], v[60:61], v[60:61], v[24:25]
	v_cvt_pk_bf16_f32 v18, v60, v61
	v_pk_fma_f32 v[24:25], v[62:63], v[62:63], v[24:25]
	v_cvt_pk_bf16_f32 v19, v62, v63
	global_store_dwordx2 v30, v[18:19], s[42:43] offset:2560 nt
	v_pk_fma_f32 v[24:25], v[64:65], v[64:65], v[24:25]
	v_cvt_pk_bf16_f32 v20, v64, v65
	v_pk_fma_f32 v[24:25], v[66:67], v[66:67], v[24:25]
	v_cvt_pk_bf16_f32 v21, v66, v67
	global_store_dwordx2 v30, v[20:21], s[42:43] offset:3072 nt
	v_pk_fma_f32 v[24:25], v[68:69], v[68:69], v[24:25]
	v_cvt_pk_bf16_f32 v22, v68, v69
	v_pk_fma_f32 v[24:25], v[70:71], v[70:71], v[24:25]
	v_cvt_pk_bf16_f32 v23, v70, v71
	global_store_dwordx2 v30, v[22:23], s[42:43] offset:3584 nt
	v_add_f32_e32 v26, v24, v25
	s_nop 1
	v_add_f32_dpp v26, v26, v26 quad_perm:[1,0,3,2] row_mask:0xf bank_mask:0xf
	s_nop 1
	v_add_f32_dpp v26, v26, v26 quad_perm:[2,3,0,1] row_mask:0xf bank_mask:0xf
	s_nop 1
	v_add_f32_dpp v26, v26, v26 row_half_mirror row_mask:0xf bank_mask:0xf
	s_nop 1
	v_add_f32_dpp v26, v26, v26 row_mirror row_mask:0xf bank_mask:0xf
	s_nop 1
	v_add_f32_dpp v26, v26, v26 row_bcast:15 row_mask:0xa bank_mask:0xf
	s_nop 1
	v_add_f32_dpp v26, v26, v26 row_bcast:31 row_mask:0xc bank_mask:0xf
	s_nop 1
	v_readlane_b32 s24, v26, 63
	s_nop 3
	v_fma_f32 v26, s24, v32, v33
	v_rsq_f32_e32 v26, v26
	s_mov_b64 exec, 1
	s_nop 1
	global_store_dword v31, v26, s[50:51]
	s_mov_b64 exec, -1
	s_branch .Lxc_exit
.Lxc_lastB:
	s_waitcnt vmcnt(0)
	s_add_i32 s22, s9, s23
	s_lshl_b32 s24, s22, 12
	s_add_u32 s42, s48, s24
	s_addc_u32 s43, s49, 0
	s_lshl_b32 s24, s22, 2
	s_add_u32 s50, s52, s24
	s_addc_u32 s51, s53, 0
	v_pk_mul_f32 v[24:25], v[72:73], v[72:73]
	v_cvt_pk_bf16_f32 v8, v72, v73
	v_pk_fma_f32 v[24:25], v[74:75], v[74:75], v[24:25]
	v_cvt_pk_bf16_f32 v9, v74, v75
	global_store_dwordx2 v30, v[8:9], s[42:43] nt
	v_pk_fma_f32 v[24:25], v[76:77], v[76:77], v[24:25]
	v_cvt_pk_bf16_f32 v10, v76, v77
	v_pk_fma_f32 v[24:25], v[78:79], v[78:79], v[24:25]
	v_cvt_pk_bf16_f32 v11, v78, v79
	global_store_dwordx2 v30, v[10:11], s[42:43] offset:512 nt
	v_pk_fma_f32 v[24:25], v[80:81], v[80:81], v[24:25]
	v_cvt_pk_bf16_f32 v12, v80, v81
	v_pk_fma_f32 v[24:25], v[82:83], v[82:83], v[24:25]
	v_cvt_pk_bf16_f32 v13, v82, v83
	global_store_dwordx2 v30, v[12:13], s[42:43] offset:1024 nt
	v_pk_fma_f32 v[24:25], v[84:85], v[84:85], v[24:25]
	v_cvt_pk_bf16_f32 v14, v84, v85
	v_pk_fma_f32 v[24:25], v[86:87], v[86:87], v[24:25]
	v_cvt_pk_bf16_f32 v15, v86, v87
	global_store_dwordx2 v30, v[14:15], s[42:43] offset:1536 nt
	v_pk_fma_f32 v[24:25], v[88:89], v[88:89], v[24:25]
	v_cvt_pk_bf16_f32 v16, v88, v89
	v_pk_fma_f32 v[24:25], v[90:91], v[90:91], v[24:25]
	v_cvt_pk_bf16_f32 v17, v90, v91
	global_store_dwordx2 v30, v[16:17], s[42:43] offset:2048 nt
	v_pk_fma_f32 v[24:25], v[92:93], v[92:93], v[24:25]
	v_cvt_pk_bf16_f32 v18, v92, v93
	v_pk_fma_f32 v[24:25], v[94:95], v[94:95], v[24:25]
	v_cvt_pk_bf16_f32 v19, v94, v95
	global_store_dwordx2 v30, v[18:19], s[42:43] offset:2560 nt
	v_pk_fma_f32 v[24:25], v[96:97], v[96:97], v[24:25]
	v_cvt_pk_bf16_f32 v20, v96, v97
	v_pk_fma_f32 v[24:25], v[98:99], v[98:99], v[24:25]
	v_cvt_pk_bf16_f32 v21, v98, v99
	global_store_dwordx2 v30, v[20:21], s[42:43] offset:3072 nt
	v_pk_fma_f32 v[24:25], v[100:101], v[100:101], v[24:25]
	v_cvt_pk_bf16_f32 v22, v100, v101
	v_pk_fma_f32 v[24:25], v[102:103], v[102:103], v[24:25]
	v_cvt_pk_bf16_f32 v23, v102, v103
	global_store_dwordx2 v30, v[22:23], s[42:43] offset:3584 nt
	v_add_f32_e32 v26, v24, v25
	s_nop 1
	v_add_f32_dpp v26, v26, v26 quad_perm:[1,0,3,2] row_mask:0xf bank_mask:0xf
	s_nop 1
	v_add_f32_dpp v26, v26, v26 quad_perm:[2,3,0,1] row_mask:0xf bank_mask:0xf
	s_nop 1
	v_add_f32_dpp v26, v26, v26 row_half_mirror row_mask:0xf bank_mask:0xf
	s_nop 1
	v_add_f32_dpp v26, v26, v26 row_mirror row_mask:0xf bank_mask:0xf
	s_nop 1
	v_add_f32_dpp v26, v26, v26 row_bcast:15 row_mask:0xa bank_mask:0xf
	s_nop 1
	v_add_f32_dpp v26, v26, v26 row_bcast:31 row_mask:0xc bank_mask:0xf
	s_nop 1
	v_readlane_b32 s24, v26, 63
	s_nop 3
	v_fma_f32 v26, s24, v32, v33
	v_rsq_f32_e32 v26, v26
	s_mov_b64 exec, 1
	s_nop 1
	global_store_dword v31, v26, s[50:51]
	s_mov_b64 exec, -1
